# same wave stagger with a shorter step (w*8*64 cycles)
# speedup vs baseline: 1.0063x; 1.0063x over previous
; #define OPAQUE_IDS int tx = threadIdx.x; int bx = blockIdx.x; asm volatile("" : "+v"(tx), "+s"(bx));
; DI void norm_phase(const Params& p, int layer, int which, bool lat_only, const float* __restrict__ part, int npart, int srcmode) {
;     OPAQUE_IDS
;     const int lane = tx & 63, gw = bx * 8 + (tx >> 6);
.Lstg_2:
	s_cmp_eq_u32 s98, 0
	s_cbranch_scc1 .Lstg_2_done
	s_sleep 8
	s_sub_u32 s98, s98, 1
	s_branch .Lstg_2
